# phase 5 tile queue: loads issued two tiles ahead (three register sets), index claims ordered before the loads so the counted wait leaves a tile in flight
# speedup vs baseline: 1.0056x; 1.0011x over previous
.Lser_exit:
	s_nop 0
	s_nop 0
	s_nop 0
	s_nop 0
	s_nop 0
	s_nop 0
	v_lshlrev_b32_e32 v157, 2, v0

.Ltq_c1:
	s_mov_b64 exec, s[26:27]
	s_waitcnt vmcnt(0)
	s_and_saveexec_b64 s[26:27], s[4:5]
	ds_write_b32 v32, v250
	s_mov_b64 exec, s[26:27]
	s_waitcnt lgkmcnt(0)
	s_barrier
	ds_read_b32 v33, v32
	s_waitcnt lgkmcnt(0)
	v_readfirstlane_b32 s6, v33
	s_nop 3
	s_cmp_ge_u32 s6, 0x780
	s_cbranch_scc1 .LBB0_571
	s_cmp_lt_u32 s6, 0x580
	s_cbranch_scc0 .Ltq_oth_p0
	s_mul_i32 s7, s6, 0x1746
	s_lshr_b32 s7, s7, 20
	s_mul_i32 s8, s7, 0xb0
	s_sub_u32 s8, s6, s8
	s_mul_i32 s9, s7, 0xb00000
	s_lshl_b32 s29, s8, 8
	s_add_u32 s9, s9, s29
	s_add_u32 s12, s52, s9
	s_addc_u32 s13, s53, 0
	s_mov_b32 s14, 0xb000
	s_mov_b32 s15, 0x160000
	s_lshl_b32 s9, s8, 18
	s_lshl_b32 s29, s7, 9
	s_add_u32 s9, s9, s29
	s_add_u32 s9, s9, 0x3a00000
	s_add_u32 s16, s70, s9
	s_addc_u32 s17, s71, 0
	s_mov_b32 s18, 12
	s_lshl_b32 s9, s7, 10
	s_add_u32 s20, s50, s9
	s_addc_u32 s21, s51, 0
	s_mov_b32 s25, 1
	s_branch .Ltq_ld_p0
.Ltq_oth_p0:
	s_sub_u32 s6, s6, 0x580
	s_cmp_lt_u32 s6, 0x100
	s_cbranch_scc0 .Ltq_out_p0
	s_lshr_b32 s30, s6, 7
	s_and_b32 s6, s6, 0x7f
	s_and_b32 s8, s6, 31
	s_lshr_b32 s7, s6, 5
	s_lshl_b32 s9, s7, 21
	s_lshl_b32 s29, s8, 8
	s_add_u32 s9, s9, s29
	s_lshl_b32 s29, s30, 23
	s_add_u32 s9, s9, s29
	s_add_u32 s12, s46, s9
	s_addc_u32 s13, s47, 0
	s_lshl_b32 s9, s8, 17
	s_lshl_b32 s29, s7, 9
	s_add_u32 s9, s9, s29
	s_lshl_b32 s29, s30, 22
	s_add_u32 s9, s9, s29
	s_add_u32 s9, s9, 0x6600000
	s_add_u32 s16, s70, s9
	s_addc_u32 s17, s71, 0
	s_mov_b32 s18, 11
	s_branch .Ltq_ns_p0
.Ltq_out_p0:
	s_sub_u32 s6, s6, 0x100
	s_and_b32 s8, s6, 31
	s_lshr_b32 s7, s6, 5
	s_lshl_b32 s9, s7, 21
	s_lshl_b32 s29, s8, 8
	s_add_u32 s9, s9, s29
	s_add_u32 s12, s48, s9
	s_addc_u32 s13, s49, 0
	s_lshl_b32 s9, s8, 18
	s_lshl_b32 s29, s7, 9
	s_add_u32 s9, s9, s29
	s_add_u32 s9, s9, 0x6e00000
	s_add_u32 s16, s70, s9
	s_addc_u32 s17, s71, 0
	s_mov_b32 s18, 12

.Ltq_ld_p0:
	v_mul_u32_u24_e32 v180, s14, v3
	v_add_u32_e32 v180, v180, v2
	v_add_u32_e32 v181, s15, v180
	v_add_u32_e32 v182, s15, v181
	v_add_u32_e32 v183, s15, v182
	v_add_u32_e32 v184, s15, v183
	v_add_u32_e32 v185, s15, v184
	v_add_u32_e32 v186, s15, v185
	v_add_u32_e32 v187, s15, v186
	s_cmp_eq_u32 s25, 0
	s_cbranch_scc1 .Ltq_one_p0
	global_load_dword v72, v28, s[20:21]
	global_load_dword v73, v28, s[20:21] offset:128
	global_load_dword v74, v28, s[20:21] offset:256
	global_load_dword v75, v28, s[20:21] offset:384
	global_load_dword v76, v28, s[20:21] offset:512
	global_load_dword v77, v28, s[20:21] offset:640
	global_load_dword v78, v28, s[20:21] offset:768
	global_load_dword v79, v28, s[20:21] offset:896
	s_branch .Ltq_sd_p0

.Ltq_sd_p0:
	global_load_dwordx4 v[40:43], v180, s[12:13]
	global_load_dwordx4 v[44:47], v181, s[12:13]
	global_load_dwordx4 v[48:51], v182, s[12:13]
	global_load_dwordx4 v[52:55], v183, s[12:13]
	global_load_dwordx4 v[56:59], v184, s[12:13]
	global_load_dwordx4 v[60:63], v185, s[12:13]
	global_load_dwordx4 v[64:67], v186, s[12:13]
	global_load_dwordx4 v[68:71], v187, s[12:13]
	s_and_saveexec_b64 s[26:27], s[4:5]
	s_cbranch_execz .Ltq_c2
	global_atomic_add v250, v37, v251, s[10:11] sc0
.Ltq_c2:
	s_mov_b64 exec, s[26:27]
	s_waitcnt vmcnt(0)
	s_and_saveexec_b64 s[26:27], s[4:5]
	ds_write_b32 v32, v250
	s_mov_b64 exec, s[26:27]
	s_waitcnt lgkmcnt(0)
	s_barrier
	ds_read_b32 v33, v32
	s_waitcnt lgkmcnt(0)
	v_readfirstlane_b32 s6, v33
	s_nop 3
	s_mov_b32 s74, 0
	s_mov_b32 s76, 0
	s_cmp_ge_u32 s6, 0x780
	s_cbranch_scc1 .Ltq_st0
	s_and_saveexec_b64 s[26:27], s[4:5]
	s_cbranch_execz .Ltq_c3
	global_atomic_add v250, v37, v251, s[10:11] sc0
.Ltq_c3:
	s_mov_b64 exec, s[26:27]
	s_cmp_lt_u32 s6, 0x580
	s_cbranch_scc0 .Ltq_oth_p1
	s_mul_i32 s7, s6, 0x1746
	s_lshr_b32 s7, s7, 20
	s_mul_i32 s8, s7, 0xb0
	s_sub_u32 s8, s6, s8
	s_mul_i32 s9, s7, 0xb00000
	s_lshl_b32 s29, s8, 8
	s_add_u32 s9, s9, s29
	s_add_u32 s12, s52, s9
	s_addc_u32 s13, s53, 0
	s_mov_b32 s14, 0xb000
	s_mov_b32 s15, 0x160000
	s_lshl_b32 s9, s8, 18
	s_lshl_b32 s29, s7, 9
	s_add_u32 s9, s9, s29
	s_add_u32 s9, s9, 0x3a00000
	s_add_u32 s22, s70, s9
	s_addc_u32 s23, s71, 0
	s_mov_b32 s24, 12
	s_lshl_b32 s9, s7, 10
	s_add_u32 s20, s50, s9
	s_addc_u32 s21, s51, 0
	s_mov_b32 s25, 1
	s_branch .Ltq_ld_p1

.Ltq_ld_p1:
	v_mul_u32_u24_e32 v180, s14, v3
	v_add_u32_e32 v180, v180, v2
	v_add_u32_e32 v181, s15, v180
	v_add_u32_e32 v182, s15, v181
	v_add_u32_e32 v183, s15, v182
	v_add_u32_e32 v184, s15, v183
	v_add_u32_e32 v185, s15, v184
	v_add_u32_e32 v186, s15, v185
	v_add_u32_e32 v187, s15, v186
	s_cmp_eq_u32 s25, 0
	s_cbranch_scc1 .Ltq_one_p1
	global_load_dword v172, v28, s[20:21]
	global_load_dword v173, v28, s[20:21] offset:128
	global_load_dword v174, v28, s[20:21] offset:256
	global_load_dword v175, v28, s[20:21] offset:384
	global_load_dword v176, v28, s[20:21] offset:512
	global_load_dword v177, v28, s[20:21] offset:640
	global_load_dword v178, v28, s[20:21] offset:768
	global_load_dword v179, v28, s[20:21] offset:896
	s_branch .Ltq_sd_p1
.Ltq_one_p1:
	v_mov_b32_e32 v172, 1.0
	v_mov_b32_e32 v173, 1.0
	v_mov_b32_e32 v174, 1.0
	v_mov_b32_e32 v175, 1.0
	v_mov_b32_e32 v176, 1.0
	v_mov_b32_e32 v177, 1.0
	v_mov_b32_e32 v178, 1.0
	v_mov_b32_e32 v179, 1.0
.Ltq_sd_p1:
	global_load_dwordx4 v[140:143], v180, s[12:13]
	global_load_dwordx4 v[144:147], v181, s[12:13]
	global_load_dwordx4 v[148:151], v182, s[12:13]
	global_load_dwordx4 v[152:155], v183, s[12:13]
	global_load_dwordx4 v[156:159], v184, s[12:13]
	global_load_dwordx4 v[160:163], v185, s[12:13]
	global_load_dwordx4 v[164:167], v186, s[12:13]
	global_load_dwordx4 v[168:171], v187, s[12:13]
	s_mov_b32 s74, 1
	s_mov_b32 s76, 1
	s_waitcnt vmcnt(8)
.Ltq_st0:
	s_mov_b32 s75, 0
	s_cmp_eq_u32 s76, 0
	s_cbranch_scc1 .Ltq_pr0
	s_and_saveexec_b64 s[26:27], s[4:5]
	ds_write_b32 v32, v250
	s_mov_b64 exec, s[26:27]
	s_waitcnt lgkmcnt(0)
	s_barrier
	ds_read_b32 v33, v32
	s_waitcnt lgkmcnt(0)
	v_readfirstlane_b32 s6, v33
	s_nop 3
	s_cmp_ge_u32 s6, 0x780
	s_cselect_b32 s76, 0, 1
	s_cbranch_scc1 .Ltq_pr0
	s_and_saveexec_b64 s[26:27], s[4:5]
	s_cbranch_execz .Ltq_c4
	global_atomic_add v250, v37, v251, s[10:11] sc0
.Ltq_c4:
	s_mov_b64 exec, s[26:27]
	s_cmp_lt_u32 s6, 0x580
	s_cbranch_scc0 .Ltq_oth_n0
	s_mul_i32 s7, s6, 0x1746
	s_lshr_b32 s7, s7, 20
	s_mul_i32 s8, s7, 0xb0
	s_sub_u32 s8, s6, s8
	s_mul_i32 s9, s7, 0xb00000
	s_lshl_b32 s29, s8, 8
	s_add_u32 s9, s9, s29
	s_add_u32 s12, s52, s9
	s_addc_u32 s13, s53, 0
	s_mov_b32 s14, 0xb000
	s_mov_b32 s15, 0x160000
	s_lshl_b32 s9, s8, 18
	s_lshl_b32 s29, s7, 9
	s_add_u32 s9, s9, s29
	s_add_u32 s9, s9, 0x3a00000
	s_add_u32 s64, s70, s9
	s_addc_u32 s65, s71, 0
	s_mov_b32 s66, 12
	s_lshl_b32 s9, s7, 10
	s_add_u32 s20, s50, s9
	s_addc_u32 s21, s51, 0
	s_mov_b32 s25, 1
	s_branch .Ltq_ld_n0
.Ltq_oth_n0:
	s_sub_u32 s6, s6, 0x580
	s_cmp_lt_u32 s6, 0x100
	s_cbranch_scc0 .Ltq_out_n0
	s_lshr_b32 s30, s6, 7
	s_and_b32 s6, s6, 0x7f
	s_and_b32 s8, s6, 31
	s_lshr_b32 s7, s6, 5
	s_lshl_b32 s9, s7, 21
	s_lshl_b32 s29, s8, 8
	s_add_u32 s9, s9, s29
	s_lshl_b32 s29, s30, 23
	s_add_u32 s9, s9, s29
	s_add_u32 s12, s46, s9
	s_addc_u32 s13, s47, 0
	s_lshl_b32 s9, s8, 17
	s_lshl_b32 s29, s7, 9
	s_add_u32 s9, s9, s29
	s_lshl_b32 s29, s30, 22
	s_add_u32 s9, s9, s29
	s_add_u32 s9, s9, 0x6600000
	s_add_u32 s64, s70, s9
	s_addc_u32 s65, s71, 0
	s_mov_b32 s66, 11
	s_branch .Ltq_ns_n0
.Ltq_out_n0:
	s_sub_u32 s6, s6, 0x100
	s_and_b32 s8, s6, 31
	s_lshr_b32 s7, s6, 5
	s_lshl_b32 s9, s7, 21
	s_lshl_b32 s29, s8, 8
	s_add_u32 s9, s9, s29
	s_add_u32 s12, s48, s9
	s_addc_u32 s13, s49, 0
	s_lshl_b32 s9, s8, 18
	s_lshl_b32 s29, s7, 9
	s_add_u32 s9, s9, s29
	s_add_u32 s9, s9, 0x6e00000
	s_add_u32 s64, s70, s9
	s_addc_u32 s65, s71, 0
	s_mov_b32 s66, 12

.Ltq_ld_n0:
	v_mul_u32_u24_e32 v180, s14, v3
	v_add_u32_e32 v180, v180, v2
	v_add_u32_e32 v181, s15, v180
	v_add_u32_e32 v182, s15, v181
	v_add_u32_e32 v183, s15, v182
	v_add_u32_e32 v184, s15, v183
	v_add_u32_e32 v185, s15, v184
	v_add_u32_e32 v186, s15, v185
	v_add_u32_e32 v187, s15, v186
	s_cmp_eq_u32 s25, 0
	s_cbranch_scc1 .Ltq_one_n0
	global_load_dword v232, v28, s[20:21]
	global_load_dword v233, v28, s[20:21] offset:128
	global_load_dword v234, v28, s[20:21] offset:256
	global_load_dword v235, v28, s[20:21] offset:384
	global_load_dword v236, v28, s[20:21] offset:512
	global_load_dword v237, v28, s[20:21] offset:640
	global_load_dword v238, v28, s[20:21] offset:768
	global_load_dword v239, v28, s[20:21] offset:896
	s_branch .Ltq_sd_n0
.Ltq_one_n0:
	v_mov_b32_e32 v232, 1.0
	v_mov_b32_e32 v233, 1.0
	v_mov_b32_e32 v234, 1.0
	v_mov_b32_e32 v235, 1.0
	v_mov_b32_e32 v236, 1.0
	v_mov_b32_e32 v237, 1.0
	v_mov_b32_e32 v238, 1.0
	v_mov_b32_e32 v239, 1.0
.Ltq_sd_n0:
	global_load_dwordx4 v[200:203], v180, s[12:13]
	global_load_dwordx4 v[204:207], v181, s[12:13]
	global_load_dwordx4 v[208:211], v182, s[12:13]
	global_load_dwordx4 v[212:215], v183, s[12:13]
	global_load_dwordx4 v[216:219], v184, s[12:13]
	global_load_dwordx4 v[220:223], v185, s[12:13]
	global_load_dwordx4 v[224:227], v186, s[12:13]
	global_load_dwordx4 v[228:231], v187, s[12:13]
	s_mov_b32 s75, 1
.Ltq_pr0:
	v_mul_f32_e32 v40, v40, v72
	v_mul_f32_e32 v41, v41, v72
	v_mul_f32_e32 v42, v42, v72
	v_mul_f32_e32 v43, v43, v72
	v_mul_f32_e32 v44, v44, v73
	v_mul_f32_e32 v45, v45, v73
	v_mul_f32_e32 v46, v46, v73
	v_mul_f32_e32 v47, v47, v73
	v_mul_f32_e32 v48, v48, v74
	v_mul_f32_e32 v49, v49, v74
	v_mul_f32_e32 v50, v50, v74
	v_mul_f32_e32 v51, v51, v74
	v_mul_f32_e32 v52, v52, v75
	v_mul_f32_e32 v53, v53, v75
	v_mul_f32_e32 v54, v54, v75
	v_mul_f32_e32 v55, v55, v75
	v_mul_f32_e32 v56, v56, v76
	v_mul_f32_e32 v57, v57, v76
	v_mul_f32_e32 v58, v58, v76
	v_mul_f32_e32 v59, v59, v76
	v_mul_f32_e32 v60, v60, v77
	v_mul_f32_e32 v61, v61, v77
	v_mul_f32_e32 v62, v62, v77
	v_mul_f32_e32 v63, v63, v77
	v_mul_f32_e32 v64, v64, v78
	v_mul_f32_e32 v65, v65, v78
	v_mul_f32_e32 v66, v66, v78
	v_mul_f32_e32 v67, v67, v78
	v_mul_f32_e32 v68, v68, v79
	v_mul_f32_e32 v69, v69, v79
	v_mul_f32_e32 v70, v70, v79
	v_mul_f32_e32 v71, v71, v79
	ds_write2_b32 v20, v40, v41 offset1:1
	ds_write2_b32 v20, v42, v43 offset0:2 offset1:3
	ds_write2_b32 v21, v44, v45 offset1:1
	ds_write2_b32 v21, v46, v47 offset0:2 offset1:3
	ds_write2_b32 v22, v48, v49 offset1:1
	ds_write2_b32 v22, v50, v51 offset0:2 offset1:3
	ds_write2_b32 v23, v52, v53 offset1:1
	ds_write2_b32 v23, v54, v55 offset0:2 offset1:3
	ds_write2_b32 v24, v56, v57 offset1:1
	ds_write2_b32 v24, v58, v59 offset0:2 offset1:3
	ds_write2_b32 v25, v60, v61 offset1:1
	ds_write2_b32 v25, v62, v63 offset0:2 offset1:3
	ds_write2_b32 v26, v64, v65 offset1:1
	ds_write2_b32 v26, v66, v67 offset0:2 offset1:3
	ds_write2_b32 v27, v68, v69 offset1:1
	ds_write2_b32 v27, v70, v71 offset0:2 offset1:3
	s_waitcnt lgkmcnt(0)
	s_barrier
	v_lshlrev_b32_e32 v29, s18, v6
	v_add_u32_e32 v29, v29, v31
	ds_read_b32 v8, v7 offset:0
	ds_read_b32 v9, v7 offset:260
	ds_read_b32 v10, v7 offset:520
	ds_read_b32 v11, v7 offset:780
	ds_read_b32 v12, v7 offset:1040
	ds_read_b32 v13, v7 offset:1300
	ds_read_b32 v14, v7 offset:1560
	ds_read_b32 v15, v7 offset:1820
	s_waitcnt lgkmcnt(0)
	v_cvt_pk_bf16_f32 v16, v8, v9
	v_cvt_pk_bf16_f32 v17, v10, v11
	v_cvt_pk_bf16_f32 v18, v12, v13
	v_cvt_pk_bf16_f32 v19, v14, v15
	global_store_dwordx4 v29, v[16:19], s[16:17]
	ds_read_b32 v8, v7 offset:16640
	ds_read_b32 v9, v7 offset:16900
	ds_read_b32 v10, v7 offset:17160
	ds_read_b32 v11, v7 offset:17420
	ds_read_b32 v12, v7 offset:17680
	ds_read_b32 v13, v7 offset:17940
	ds_read_b32 v14, v7 offset:18200
	ds_read_b32 v15, v7 offset:18460
	s_waitcnt lgkmcnt(0)
	v_cvt_pk_bf16_f32 v100, v8, v9
	v_cvt_pk_bf16_f32 v101, v10, v11
	v_cvt_pk_bf16_f32 v102, v12, v13
	v_cvt_pk_bf16_f32 v103, v14, v15
	global_store_dwordx4 v29, v[100:103], s[16:17] offset:128
	ds_read_b32 v8, v7 offset:33280
	ds_read_b32 v9, v7 offset:33540
	ds_read_b32 v10, v7 offset:33800
	ds_read_b32 v11, v7 offset:34060
	ds_read_b32 v12, v7 offset:34320
	ds_read_b32 v13, v7 offset:34580
	ds_read_b32 v14, v7 offset:34840
	ds_read_b32 v15, v7 offset:35100
	s_waitcnt lgkmcnt(0)
	v_cvt_pk_bf16_f32 v104, v8, v9
	v_cvt_pk_bf16_f32 v105, v10, v11
	v_cvt_pk_bf16_f32 v106, v12, v13
	v_cvt_pk_bf16_f32 v107, v14, v15
	global_store_dwordx4 v29, v[104:107], s[16:17] offset:256
	ds_read_b32 v8, v7 offset:49920
	ds_read_b32 v9, v7 offset:50180
	ds_read_b32 v10, v7 offset:50440
	ds_read_b32 v11, v7 offset:50700
	ds_read_b32 v12, v7 offset:50960
	ds_read_b32 v13, v7 offset:51220
	ds_read_b32 v14, v7 offset:51480
	ds_read_b32 v15, v7 offset:51740
	s_waitcnt lgkmcnt(0)
	v_cvt_pk_bf16_f32 v108, v8, v9
	v_cvt_pk_bf16_f32 v109, v10, v11
	v_cvt_pk_bf16_f32 v110, v12, v13
	v_cvt_pk_bf16_f32 v111, v14, v15
	global_store_dwordx4 v29, v[108:111], s[16:17] offset:384
	s_barrier
	s_cmp_eq_u32 s74, 0
	s_cbranch_scc1 .LBB0_571
	s_mov_b32 s74, s75
	s_cmp_eq_u32 s75, 0
	s_cbranch_scc1 .Ltq_w4_0
	s_waitcnt vmcnt(12)
	s_branch .Ltq_st1
.Ltq_w4_0:
	s_waitcnt vmcnt(4)
	s_branch .Ltq_st1

.Ltq_c5:
	s_mov_b64 exec, s[26:27]
	s_cmp_lt_u32 s6, 0x580
	s_cbranch_scc0 .Ltq_oth_n1
	s_mul_i32 s7, s6, 0x1746
	s_lshr_b32 s7, s7, 20
	s_mul_i32 s8, s7, 0xb0
	s_sub_u32 s8, s6, s8
	s_mul_i32 s9, s7, 0xb00000
	s_lshl_b32 s29, s8, 8
	s_add_u32 s9, s9, s29
	s_add_u32 s12, s52, s9
	s_addc_u32 s13, s53, 0
	s_mov_b32 s14, 0xb000
	s_mov_b32 s15, 0x160000
	s_lshl_b32 s9, s8, 18
	s_lshl_b32 s29, s7, 9
	s_add_u32 s9, s9, s29
	s_add_u32 s9, s9, 0x3a00000
	s_add_u32 s16, s70, s9
	s_addc_u32 s17, s71, 0
	s_mov_b32 s18, 12
	s_lshl_b32 s9, s7, 10
	s_add_u32 s20, s50, s9
	s_addc_u32 s21, s51, 0
	s_mov_b32 s25, 1
	s_branch .Ltq_ld_n1

.Ltq_sd_n1:
	global_load_dwordx4 v[40:43], v180, s[12:13]
	global_load_dwordx4 v[44:47], v181, s[12:13]
	global_load_dwordx4 v[48:51], v182, s[12:13]
	global_load_dwordx4 v[52:55], v183, s[12:13]
	global_load_dwordx4 v[56:59], v184, s[12:13]
	global_load_dwordx4 v[60:63], v185, s[12:13]
	global_load_dwordx4 v[64:67], v186, s[12:13]
	global_load_dwordx4 v[68:71], v187, s[12:13]
	s_mov_b32 s75, 1
.Ltq_pr1:
	v_mul_f32_e32 v140, v140, v172
	v_mul_f32_e32 v141, v141, v172
	v_mul_f32_e32 v142, v142, v172
	v_mul_f32_e32 v143, v143, v172
	v_mul_f32_e32 v144, v144, v173
	v_mul_f32_e32 v145, v145, v173
	v_mul_f32_e32 v146, v146, v173
	v_mul_f32_e32 v147, v147, v173
	v_mul_f32_e32 v148, v148, v174
	v_mul_f32_e32 v149, v149, v174
	v_mul_f32_e32 v150, v150, v174
	v_mul_f32_e32 v151, v151, v174
	v_mul_f32_e32 v152, v152, v175
	v_mul_f32_e32 v153, v153, v175
	v_mul_f32_e32 v154, v154, v175
	v_mul_f32_e32 v155, v155, v175
	v_mul_f32_e32 v156, v156, v176
	v_mul_f32_e32 v157, v157, v176
	v_mul_f32_e32 v158, v158, v176
	v_mul_f32_e32 v159, v159, v176
	v_mul_f32_e32 v160, v160, v177
	v_mul_f32_e32 v161, v161, v177
	v_mul_f32_e32 v162, v162, v177
	v_mul_f32_e32 v163, v163, v177
	v_mul_f32_e32 v164, v164, v178
	v_mul_f32_e32 v165, v165, v178
	v_mul_f32_e32 v166, v166, v178
	v_mul_f32_e32 v167, v167, v178
	v_mul_f32_e32 v168, v168, v179
	v_mul_f32_e32 v169, v169, v179
	v_mul_f32_e32 v170, v170, v179
	v_mul_f32_e32 v171, v171, v179
	ds_write2_b32 v20, v140, v141 offset1:1
	ds_write2_b32 v20, v142, v143 offset0:2 offset1:3
	ds_write2_b32 v21, v144, v145 offset1:1
	ds_write2_b32 v21, v146, v147 offset0:2 offset1:3
	ds_write2_b32 v22, v148, v149 offset1:1
	ds_write2_b32 v22, v150, v151 offset0:2 offset1:3
	ds_write2_b32 v23, v152, v153 offset1:1
	ds_write2_b32 v23, v154, v155 offset0:2 offset1:3
	ds_write2_b32 v24, v156, v157 offset1:1
	ds_write2_b32 v24, v158, v159 offset0:2 offset1:3
	ds_write2_b32 v25, v160, v161 offset1:1
	ds_write2_b32 v25, v162, v163 offset0:2 offset1:3
	ds_write2_b32 v26, v164, v165 offset1:1
	ds_write2_b32 v26, v166, v167 offset0:2 offset1:3
	ds_write2_b32 v27, v168, v169 offset1:1
	ds_write2_b32 v27, v170, v171 offset0:2 offset1:3
	s_waitcnt lgkmcnt(0)
	s_barrier
	v_lshlrev_b32_e32 v29, s24, v6
	v_add_u32_e32 v29, v29, v31
	ds_read_b32 v8, v7 offset:0
	ds_read_b32 v9, v7 offset:260
	ds_read_b32 v10, v7 offset:520
	ds_read_b32 v11, v7 offset:780
	ds_read_b32 v12, v7 offset:1040
	ds_read_b32 v13, v7 offset:1300
	ds_read_b32 v14, v7 offset:1560
	ds_read_b32 v15, v7 offset:1820
	s_waitcnt lgkmcnt(0)
	v_cvt_pk_bf16_f32 v16, v8, v9
	v_cvt_pk_bf16_f32 v17, v10, v11
	v_cvt_pk_bf16_f32 v18, v12, v13
	v_cvt_pk_bf16_f32 v19, v14, v15
	global_store_dwordx4 v29, v[16:19], s[22:23]
	ds_read_b32 v8, v7 offset:16640
	ds_read_b32 v9, v7 offset:16900
	ds_read_b32 v10, v7 offset:17160
	ds_read_b32 v11, v7 offset:17420
	ds_read_b32 v12, v7 offset:17680
	ds_read_b32 v13, v7 offset:17940
	ds_read_b32 v14, v7 offset:18200
	ds_read_b32 v15, v7 offset:18460
	s_waitcnt lgkmcnt(0)
	v_cvt_pk_bf16_f32 v100, v8, v9
	v_cvt_pk_bf16_f32 v101, v10, v11
	v_cvt_pk_bf16_f32 v102, v12, v13
	v_cvt_pk_bf16_f32 v103, v14, v15
	global_store_dwordx4 v29, v[100:103], s[22:23] offset:128
	ds_read_b32 v8, v7 offset:33280
	ds_read_b32 v9, v7 offset:33540
	ds_read_b32 v10, v7 offset:33800
	ds_read_b32 v11, v7 offset:34060
	ds_read_b32 v12, v7 offset:34320
	ds_read_b32 v13, v7 offset:34580
	ds_read_b32 v14, v7 offset:34840
	ds_read_b32 v15, v7 offset:35100
	s_waitcnt lgkmcnt(0)
	v_cvt_pk_bf16_f32 v104, v8, v9
	v_cvt_pk_bf16_f32 v105, v10, v11
	v_cvt_pk_bf16_f32 v106, v12, v13
	v_cvt_pk_bf16_f32 v107, v14, v15
	global_store_dwordx4 v29, v[104:107], s[22:23] offset:256
	ds_read_b32 v8, v7 offset:49920
	ds_read_b32 v9, v7 offset:50180
	ds_read_b32 v10, v7 offset:50440
	ds_read_b32 v11, v7 offset:50700
	ds_read_b32 v12, v7 offset:50960
	ds_read_b32 v13, v7 offset:51220
	ds_read_b32 v14, v7 offset:51480
	ds_read_b32 v15, v7 offset:51740
	s_waitcnt lgkmcnt(0)
	v_cvt_pk_bf16_f32 v108, v8, v9
	v_cvt_pk_bf16_f32 v109, v10, v11
	v_cvt_pk_bf16_f32 v110, v12, v13
	v_cvt_pk_bf16_f32 v111, v14, v15
	global_store_dwordx4 v29, v[108:111], s[22:23] offset:384
	s_barrier
	s_cmp_eq_u32 s74, 0
	s_cbranch_scc1 .LBB0_571
	s_mov_b32 s74, s75
	s_cmp_eq_u32 s75, 0
	s_cbranch_scc1 .Ltq_w4_1
	s_waitcnt vmcnt(12)
	s_branch .Ltq_st2

.Ltq_sd_n2:
	global_load_dwordx4 v[140:143], v180, s[12:13]
	global_load_dwordx4 v[144:147], v181, s[12:13]
	global_load_dwordx4 v[148:151], v182, s[12:13]
	global_load_dwordx4 v[152:155], v183, s[12:13]
	global_load_dwordx4 v[156:159], v184, s[12:13]
	global_load_dwordx4 v[160:163], v185, s[12:13]
	global_load_dwordx4 v[164:167], v186, s[12:13]
	global_load_dwordx4 v[168:171], v187, s[12:13]
	s_mov_b32 s75, 1
.Ltq_pr2:
	v_mul_f32_e32 v200, v200, v232
	v_mul_f32_e32 v201, v201, v232
	v_mul_f32_e32 v202, v202, v232
	v_mul_f32_e32 v203, v203, v232
	v_mul_f32_e32 v204, v204, v233
	v_mul_f32_e32 v205, v205, v233
	v_mul_f32_e32 v206, v206, v233
	v_mul_f32_e32 v207, v207, v233
	v_mul_f32_e32 v208, v208, v234
	v_mul_f32_e32 v209, v209, v234
	v_mul_f32_e32 v210, v210, v234
	v_mul_f32_e32 v211, v211, v234
	v_mul_f32_e32 v212, v212, v235
	v_mul_f32_e32 v213, v213, v235
	v_mul_f32_e32 v214, v214, v235
	v_mul_f32_e32 v215, v215, v235
	v_mul_f32_e32 v216, v216, v236
	v_mul_f32_e32 v217, v217, v236
	v_mul_f32_e32 v218, v218, v236
	v_mul_f32_e32 v219, v219, v236
	v_mul_f32_e32 v220, v220, v237
	v_mul_f32_e32 v221, v221, v237
	v_mul_f32_e32 v222, v222, v237
	v_mul_f32_e32 v223, v223, v237
	v_mul_f32_e32 v224, v224, v238
	v_mul_f32_e32 v225, v225, v238
	v_mul_f32_e32 v226, v226, v238
	v_mul_f32_e32 v227, v227, v238
	v_mul_f32_e32 v228, v228, v239
	v_mul_f32_e32 v229, v229, v239
	v_mul_f32_e32 v230, v230, v239
	v_mul_f32_e32 v231, v231, v239
	ds_write2_b32 v20, v200, v201 offset1:1
	ds_write2_b32 v20, v202, v203 offset0:2 offset1:3
	ds_write2_b32 v21, v204, v205 offset1:1
	ds_write2_b32 v21, v206, v207 offset0:2 offset1:3
	ds_write2_b32 v22, v208, v209 offset1:1
	ds_write2_b32 v22, v210, v211 offset0:2 offset1:3
	ds_write2_b32 v23, v212, v213 offset1:1
	ds_write2_b32 v23, v214, v215 offset0:2 offset1:3
	ds_write2_b32 v24, v216, v217 offset1:1
	ds_write2_b32 v24, v218, v219 offset0:2 offset1:3
	ds_write2_b32 v25, v220, v221 offset1:1
	ds_write2_b32 v25, v222, v223 offset0:2 offset1:3
	ds_write2_b32 v26, v224, v225 offset1:1
	ds_write2_b32 v26, v226, v227 offset0:2 offset1:3
	ds_write2_b32 v27, v228, v229 offset1:1
	ds_write2_b32 v27, v230, v231 offset0:2 offset1:3
	s_waitcnt lgkmcnt(0)
	s_barrier
	v_lshlrev_b32_e32 v29, s66, v6
	v_add_u32_e32 v29, v29, v31
	ds_read_b32 v8, v7 offset:0
	ds_read_b32 v9, v7 offset:260
	ds_read_b32 v10, v7 offset:520
	ds_read_b32 v11, v7 offset:780
	ds_read_b32 v12, v7 offset:1040
	ds_read_b32 v13, v7 offset:1300
	ds_read_b32 v14, v7 offset:1560
	ds_read_b32 v15, v7 offset:1820
	s_waitcnt lgkmcnt(0)
	v_cvt_pk_bf16_f32 v16, v8, v9
	v_cvt_pk_bf16_f32 v17, v10, v11
	v_cvt_pk_bf16_f32 v18, v12, v13
	v_cvt_pk_bf16_f32 v19, v14, v15
	global_store_dwordx4 v29, v[16:19], s[64:65]
	ds_read_b32 v8, v7 offset:16640
	ds_read_b32 v9, v7 offset:16900
	ds_read_b32 v10, v7 offset:17160
	ds_read_b32 v11, v7 offset:17420
	ds_read_b32 v12, v7 offset:17680
	ds_read_b32 v13, v7 offset:17940
	ds_read_b32 v14, v7 offset:18200
	ds_read_b32 v15, v7 offset:18460
	s_waitcnt lgkmcnt(0)
	v_cvt_pk_bf16_f32 v100, v8, v9
	v_cvt_pk_bf16_f32 v101, v10, v11
	v_cvt_pk_bf16_f32 v102, v12, v13
	v_cvt_pk_bf16_f32 v103, v14, v15
	global_store_dwordx4 v29, v[100:103], s[64:65] offset:128
	ds_read_b32 v8, v7 offset:33280
	ds_read_b32 v9, v7 offset:33540
	ds_read_b32 v10, v7 offset:33800
	ds_read_b32 v11, v7 offset:34060
	ds_read_b32 v12, v7 offset:34320
	ds_read_b32 v13, v7 offset:34580
	ds_read_b32 v14, v7 offset:34840
	ds_read_b32 v15, v7 offset:35100
	s_waitcnt lgkmcnt(0)
	v_cvt_pk_bf16_f32 v104, v8, v9
	v_cvt_pk_bf16_f32 v105, v10, v11
	v_cvt_pk_bf16_f32 v106, v12, v13
	v_cvt_pk_bf16_f32 v107, v14, v15
	global_store_dwordx4 v29, v[104:107], s[64:65] offset:256
	ds_read_b32 v8, v7 offset:49920
	ds_read_b32 v9, v7 offset:50180
	ds_read_b32 v10, v7 offset:50440
	ds_read_b32 v11, v7 offset:50700
	ds_read_b32 v12, v7 offset:50960
	ds_read_b32 v13, v7 offset:51220
	ds_read_b32 v14, v7 offset:51480
	ds_read_b32 v15, v7 offset:51740
	s_waitcnt lgkmcnt(0)
	v_cvt_pk_bf16_f32 v108, v8, v9
	v_cvt_pk_bf16_f32 v109, v10, v11
	v_cvt_pk_bf16_f32 v110, v12, v13
	v_cvt_pk_bf16_f32 v111, v14, v15
	global_store_dwordx4 v29, v[108:111], s[64:65] offset:384
	s_barrier
	s_cmp_eq_u32 s74, 0
	s_cbranch_scc1 .LBB0_571
	s_mov_b32 s74, s75
	s_cmp_eq_u32 s75, 0
	s_cbranch_scc1 .Ltq_w4_2
	s_waitcnt vmcnt(12)
	s_branch .Ltq_st0
